# v16 + cross-attention phase: second half of the grid runs its sample-row (cache-streaming) item before its 256-token MFMA item, mixing item types per CU
# speedup vs baseline: 1.0132x; 1.0009x over previous
; DEVI void run_phase(const Params& p, int ph, char* smem) {
;     ...
;       for (int it = blockIdx.x; it < 512 + 512; it += G) {
;         if (it < 512) {
;           const int hf = it & 1, i2 = it >> 1;
;           const int b = i2 >> 5, h = (i2 >> 3) & 3, tb = i2 & 7;
;           const u16* Kb = mkv + ((size_t)(0 * 4 + l) * 2048 + b * 256) * 256 + h * 64;
;           const u16* Vb = mkv + ((size_t)(4 + l) * 2048 + b * 256) * 256 + h * 64;
;           const size_t qo = (size_t)(b * 2048 + tb * 256) * 256 + h * 64;
;           attn256_item(Kb, 256, Vb, 0, qx + qo, 256, ox + qo, 256, 0, 0.f, 0.f, 0.f, 0.f, smem, hf * 2, hf * 2 + 2);
.LBB0_225:
	s_andn2_b64 vcc, exec, s[2:3]
	s_cbranch_vccnz .LBB0_711
	v_readlane_b32 s2, v251, 17
	v_readlane_b32 s3, v251, 18
	s_andn2_b64 vcc, exec, s[2:3]
	s_cbranch_vccnz .LBB0_711
	v_readlane_b32 s3, v254, 62
	s_and_b32 s0, 0xffff, s3
	s_lshl_b32 s2, s0, 20
	v_readlane_b32 s4, v251, 19
	v_readlane_b32 s5, v251, 20
	s_add_u32 s2, s4, s2
	v_writelane_b32 v255, s2, 2
	s_addc_u32 s2, s5, 0
	v_writelane_b32 v255, s2, 18
	s_lshl_b32 s2, s3, 20
	s_add_u32 s2, s4, s2
	s_addc_u32 s3, s5, 0
	s_add_u32 s2, s2, 0x400000
	v_writelane_b32 v255, s2, 22
	s_addc_u32 s2, s3, 0
	v_writelane_b32 v255, s2, 24
	s_lshl_b32 s0, s0, 15
	v_writelane_b32 v255, s0, 26
	v_readlane_b32 s0, v251, 21
	v_readlane_b32 s37, v250, 0
	s_nop 0
	v_writelane_b32 v255, s0, 17
	v_readlane_b32 s2, v250, 7
	s_cmpk_lg_u32 s2, 0x200
	s_cbranch_scc1 .Lxr_e
	s_cmpk_lt_u32 s37, 0x100
	s_cbranch_scc1 .Lxr_e
	s_add_i32 s37, s37, s2
	v_readlane_b32 s3, v251, 22
	s_add_i32 s0, s0, s3
	v_writelane_b32 v255, s0, 17

; DEVI void run_phase(const Params& p, int ph, char* smem) {
;     ...
;       for (int it = blockIdx.x; it < 512 + 512; it += G) {
.LBB0_228:
	v_readlane_b32 s4, v250, 1
	v_readlane_b32 s10, v250, 7
	v_readlane_b32 s0, v251, 22
	v_readlane_b32 s2, v255, 17
	s_cmpk_lg_u32 s10, 0x200
	s_cbranch_scc1 .Lxr_std
	v_readlane_b32 s5, v250, 0
	s_cmpk_lt_u32 s5, 0x100
	s_cbranch_scc1 .Lxr_std
	s_cmpk_lt_u32 s37, 0x200
	s_cbranch_scc1 .Lxr_done
	s_sub_i32 s37, s37, s10
	s_sub_i32 s2, s2, s0
	v_writelane_b32 v255, s2, 17
	s_branch .Lxr_join
.Lxr_done:
	s_movk_i32 s37, 0x400
	s_branch .Lxr_join
.Lxr_std:
	s_add_i32 s37, s37, s10
	s_add_i32 s2, s2, s0
	v_writelane_b32 v255, s2, 17
.Lxr_join:
	s_cmpk_gt_i32 s37, 0x3ff
	v_readlane_b32 s5, v250, 2
	v_readlane_b32 s6, v250, 3
	v_readlane_b32 s7, v250, 4
	v_readlane_b32 s8, v250, 5
	v_readlane_b32 s9, v250, 6
	v_readlane_b32 s11, v250, 8
	s_cbranch_scc1 .LBB0_711
